# nine split barriers, no placement pad (hand-written glds loop heads at 0 mod 8 bytes)
# speedup vs baseline: 1.0068x; 1.0068x over previous
.Lsb1_skip:
	s_cmp_gt_i32 s89, 2
	s_cselect_b64 s[4:5], -1, 0
	s_waitcnt lgkmcnt(0)
	s_cmp_lt_i32 s88, 3
	s_cselect_b64 s[18:19], -1, 0
	s_and_b64 s[4:5], s[18:19], s[4:5]
	s_andn2_b64 vcc, exec, s[4:5]
	s_cbranch_vccnz .LBB0_426
	s_add_u32 s16, s34, 0x28c4000
	s_addc_u32 s17, s35, 0
	s_add_u32 s6, s34, 0x8a44000
	s_addc_u32 s7, s35, 0
	s_add_u32 s8, s0, 0x120
	s_addc_u32 s9, s1, 0
	s_cmpk_lt_i32 s2, 0x100
	s_cbranch_scc0 .LBB0_197
	s_load_dword s9, s[0:1], 0x120
	v_readfirstlane_b32 s42, v205
	v_and_b32_e32 v192, 15, v204
	v_bfe_u32 v193, v204, 4, 2
	v_lshrrev_b32_e32 v194, 8, v204
	v_bfe_u32 v195, v204, 6, 2
	v_bfe_u32 v196, v204, 1, 3
	v_xor_b32_e32 v197, v193, v196
	v_xor_b32_e32 v198, 4, v197
	v_lshlrev_b32_e32 v197, 4, v197
	v_lshlrev_b32_e32 v198, 4, v198
	v_lshlrev_b32_e32 v199, 14, v194
	v_lshl_add_u32 v199, v192, 7, v199
	v_add_u32_e32 v242, v199, v197
	v_add_u32_e32 v243, v199, v198
	v_lshlrev_b32_e32 v199, 13, v195
	v_lshl_add_u32 v199, v192, 7, v199
	v_add_u32_e32 v199, 0x8000, v199
	v_add_u32_e32 v244, v199, v197
	v_add_u32_e32 v245, v199, v198
	v_add_u32_e32 v246, 0x10000, v242
	v_add_u32_e32 v248, 0x10000, v244
	v_add_u32_e32 v247, 0x10000, v243
	v_add_u32_e32 v249, 0x10000, v245
	v_lshrrev_b32_e32 v199, 3, v204
	v_and_b32_e32 v200, 7, v204
	v_bfe_u32 v201, v204, 4, 3
	v_xor_b32_e32 v200, v200, v201
	v_lshlrev_b32_e32 v200, 4, v200
	v_lshl_add_u32 v238, v199, 11, v200
	v_add_u32_e32 v239, 0x20000, v238
	v_add_u32_e32 v240, 0x40000, v238
	v_add_u32_e32 v241, 0x60000, v238
	s_lshl_b32 s42, s42, 10
	s_mov_b32 s8, s2
	s_and_b32 s44, s8, 7
	s_lshl_b32 s44, s44, 5
	s_lshr_b32 s45, s8, 3
	s_add_i32 s44, s44, s45
	s_lshr_b32 s45, s44, 6
	s_and_b32 s44, s44, 63
	s_and_b32 s98, s44, 7
	s_lshl_b32 s45, s45, 3
	s_add_i32 s45, s45, s98
	s_lshl_b32 s14, s45, 8
	s_lshr_b32 s44, s44, 3
	s_lshl_b32 s15, s44, 8
	s_mul_i32 s44, s14, 0x800
	s_add_u32 s44, s44, 0x8a44000
	s_add_u32 s10, s34, s44
	s_addc_u32 s11, s35, 0
	s_mul_i32 s44, s15, 0x800
	s_add_u32 s44, s44, 0x0
	s_add_u32 s12, s34, s44
	s_addc_u32 s13, s35, 0
	s_waitcnt vmcnt(0) lgkmcnt(0)
	s_barrier
	s_add_u32 m0, s42, 0x0
	s_nop 0
	global_load_lds_dwordx4 v238, s[10:11]
	s_add_u32 m0, s42, 0x2000
	s_nop 0
	global_load_lds_dwordx4 v239, s[10:11]
	s_add_u32 m0, s42, 0x4000
	s_nop 0
	global_load_lds_dwordx4 v240, s[10:11]
	s_add_u32 m0, s42, 0x6000
	s_nop 0
	global_load_lds_dwordx4 v241, s[10:11]
	s_add_u32 m0, s42, 0x8000
	s_nop 0
	global_load_lds_dwordx4 v238, s[12:13]
	s_add_u32 m0, s42, 0xa000
	s_nop 0
	global_load_lds_dwordx4 v239, s[12:13]
	s_add_u32 m0, s42, 0xc000
	s_nop 0
	global_load_lds_dwordx4 v240, s[12:13]
	s_add_u32 m0, s42, 0xe000
	s_nop 0
	global_load_lds_dwordx4 v241, s[12:13]
	s_waitcnt vmcnt(0)
.Lgl_tile_proj:
	s_add_i32 s43, s8, s9
	s_cmpk_lt_i32 s43, 256
	s_cselect_b64 s[26:27], 0, -1
	s_cbranch_scc0 .Lgl_nonext_proj
	s_and_b32 s44, s43, 7
	s_lshl_b32 s44, s44, 5
	s_lshr_b32 s45, s43, 3
	s_add_i32 s44, s44, s45
	s_lshr_b32 s45, s44, 6
	s_and_b32 s44, s44, 63
	s_and_b32 s98, s44, 7
	s_lshl_b32 s45, s45, 3
	s_add_i32 s45, s45, s98
	s_lshl_b32 s20, s45, 8
	s_lshr_b32 s44, s44, 3
	s_lshl_b32 s21, s44, 8
	s_mul_i32 s44, s20, 0x800
	s_add_u32 s44, s44, 0x8a44000
	s_add_u32 s22, s34, s44
	s_addc_u32 s23, s35, 0
	s_mul_i32 s44, s21, 0x800
	s_add_u32 s44, s44, 0x0
	s_add_u32 s24, s34, s44
	s_addc_u32 s25, s35, 0
	s_branch .Lgl_havenext_proj
